# v2: v1 + S5 table section of phase 0 de-serialised (64 loads issued together instead of 48 dependent round trips on blocks 0-7)
# speedup vs baseline: 1.0262x; 1.0030x over previous
.LBB0_123:
	s_or_b64 exec, exec, s[0:1]
	v_ldexp_f64 v[80:81], v[74:75], 6
	v_mul_f64 v[58:59], v[80:81], v[58:59]
	v_mul_f64 v[80:81], v[58:59], s[24:25]
	v_rndne_f64_e32 v[80:81], v[80:81]
	v_fma_f64 v[82:83], s[26:27], v[80:81], v[58:59]
	v_fmac_f64_e32 v[82:83], s[28:29], v[80:81]
	v_mov_b64_e32 v[84:85], v[14:15]
	v_fmac_f64_e32 v[84:85], s[30:31], v[82:83]
	v_mov_b64_e32 v[86:87], v[16:17]
	v_fmac_f64_e32 v[86:87], v[82:83], v[84:85]
	v_mov_b64_e32 v[84:85], v[18:19]
	v_fmac_f64_e32 v[84:85], v[82:83], v[86:87]
	v_mov_b64_e32 v[86:87], v[20:21]
	v_fmac_f64_e32 v[86:87], v[82:83], v[84:85]
	v_mov_b64_e32 v[84:85], v[22:23]
	v_fmac_f64_e32 v[84:85], v[82:83], v[86:87]
	v_mov_b64_e32 v[86:87], v[24:25]
	v_fmac_f64_e32 v[86:87], v[82:83], v[84:85]
	v_mov_b64_e32 v[84:85], v[26:27]
	v_fmac_f64_e32 v[84:85], v[82:83], v[86:87]
	v_mov_b64_e32 v[86:87], v[28:29]
	v_fmac_f64_e32 v[86:87], v[82:83], v[84:85]
	v_mov_b64_e32 v[84:85], v[30:31]
	v_fmac_f64_e32 v[84:85], v[82:83], v[86:87]
	v_fma_f64 v[84:85], v[82:83], v[84:85], 1.0
	v_fma_f64 v[82:83], v[82:83], v[84:85], 1.0
	v_cvt_i32_f64_e32 v3, v[80:81]
	v_ldexp_f64 v[80:81], v[82:83], v3
	v_cmp_nlt_f64_e32 vcc, s[80:81], v[58:59]
	v_cmp_ngt_f64_e64 s[0:1], s[82:83], v[58:59]
	v_add_f64 v[62:63], v[62:63], -1.0
	v_cndmask_b32_e32 v3, v4, v81, vcc
	s_and_b64 vcc, s[0:1], vcc
	v_cndmask_b32_e64 v59, 0, v3, s[0:1]
	v_cndmask_b32_e32 v58, 0, v80, vcc
	v_mul_f64 v[78:79], v[58:59], v[78:79]
	v_mul_f64 v[58:59], v[58:59], v[64:65]
	v_cvt_f32_f64_e32 v78, v[78:79]
	v_cvt_f32_f64_e32 v79, v[58:59]
	v_add_co_u32_e32 v58, vcc, s88, v60
	v_mul_f64 v[80:81], v[62:63], v[74:75]
	s_nop 0
	v_addc_co_u32_e32 v59, vcc, 0, v61, vcc
	global_store_dwordx2 v[58:59], v[78:79], off offset:3072
	v_lshl_add_u64 v[60:61], s[52:53], 0, v[12:13]
	v_lshl_add_u64 v[58:59], s[50:51], 0, v[12:13]
	global_load_dword v41, v[60:61], off
	global_load_dword v3, v[58:59], off
	v_mul_f64 v[78:79], v[72:73], v[72:73]
	v_fmac_f64_e32 v[78:79], v[74:75], v[74:75]
	v_mul_f64 v[82:83], v[62:63], v[72:73]
	v_fmac_f64_e32 v[80:81], v[76:77], v[72:73]
	v_fma_f64 v[74:75], v[76:77], v[74:75], -v[82:83]
	v_div_scale_f64 v[72:73], s[0:1], v[78:79], v[78:79], v[80:81]
	v_div_scale_f64 v[86:87], s[0:1], v[78:79], v[78:79], v[74:75]
	v_rcp_f64_e32 v[88:89], v[72:73]
	v_rcp_f64_e32 v[90:91], v[86:87]
	v_lshl_add_u64 v[64:65], s[74:75], 0, v[12:13]
	v_add_co_u32_e32 v62, vcc, s89, v64
	v_fma_f64 v[94:95], -v[72:73], v[88:89], 1.0
	s_nop 0
	v_addc_co_u32_e32 v63, vcc, 0, v65, vcc
	v_add_co_u32_e32 v64, vcc, s90, v64
	v_fma_f64 v[96:97], -v[86:87], v[90:91], 1.0
	v_fmac_f64_e32 v[88:89], v[88:89], v[94:95]
	v_addc_co_u32_e32 v65, vcc, 0, v65, vcc
	v_fmac_f64_e32 v[90:91], v[90:91], v[96:97]
	v_fma_f64 v[94:95], -v[72:73], v[88:89], 1.0
	v_div_scale_f64 v[82:83], vcc, v[80:81], v[78:79], v[80:81]
	v_fma_f64 v[96:97], -v[86:87], v[90:91], 1.0
	v_fmac_f64_e32 v[88:89], v[88:89], v[94:95]
	v_div_scale_f64 v[92:93], s[0:1], v[74:75], v[78:79], v[74:75]
	v_fmac_f64_e32 v[90:91], v[90:91], v[96:97]
	v_mul_f64 v[94:95], v[82:83], v[88:89]
	v_mul_f64 v[96:97], v[92:93], v[90:91]
	v_fma_f64 v[72:73], -v[72:73], v[94:95], v[82:83]
	v_fma_f64 v[82:83], -v[86:87], v[96:97], v[92:93]
	v_div_fmas_f64 v[72:73], v[72:73], v[88:89], v[94:95]
	s_mov_b64 vcc, s[0:1]
	v_div_fixup_f64 v[72:73], v[72:73], v[78:79], v[80:81]
	v_div_fmas_f64 v[80:81], v[82:83], v[90:91], v[96:97]
	v_div_fixup_f64 v[74:75], v[80:81], v[78:79], v[74:75]
	v_lshlrev_b64 v[56:57], 12, v[56:57]
	v_or_b32_e32 v84, v56, v69
	v_mov_b32_e32 v85, v57
	v_lshl_add_u64 v[76:77], s[54:55], 0, v[84:85]
	v_lshl_add_u64 v[54:55], v[54:55], 0, s[60:61]
	v_cmp_lt_u64_e32 vcc, s[84:85], v[54:55]
	v_lshl_add_u64 v[8:9], v[8:9], 0, s[10:11]
	v_lshl_add_u64 v[10:11], v[10:11], 0, s[12:13]
	s_or_b64 s[22:23], vcc, s[22:23]
	v_lshl_add_u64 v[12:13], v[12:13], 0, s[14:15]
	s_waitcnt vmcnt(1)
	v_cvt_f64_f32_e32 v[80:81], v41
	s_waitcnt vmcnt(0)
	v_cvt_f64_f32_e32 v[78:79], v3
	v_mul_f64 v[82:83], v[74:75], v[80:81]
	v_mul_f64 v[80:81], v[72:73], v[80:81]
	v_fma_f64 v[82:83], v[72:73], v[78:79], -v[82:83]
	v_fmac_f64_e32 v[80:81], v[74:75], v[78:79]
	v_cvt_f32_f64_e32 v3, v[82:83]
	v_cvt_f32_f64_e32 v41, v[80:81]
	global_store_dword v[62:63], v3, off offset:3072
	global_store_dword v[64:65], v41, off offset:3072
	global_load_dwordx4 v[176:179], v[58:59], off
	global_load_dwordx4 v[140:143], v[60:61], off
	global_load_dwordx4 v[180:183], v[58:59], off offset:16
	global_load_dwordx4 v[144:147], v[60:61], off offset:16
	global_load_dwordx4 v[184:187], v[58:59], off offset:32
	global_load_dwordx4 v[148:151], v[60:61], off offset:32
	global_load_dwordx4 v[188:191], v[58:59], off offset:48
	global_load_dwordx4 v[152:155], v[60:61], off offset:48
	v_lshl_add_u64 v[78:79], s[56:57], 0, v[84:85]
	global_load_dword v90, v[76:77], off
	global_load_dword v106, v[78:79], off
	global_load_dword v91, v[76:77], off offset:256
	global_load_dword v107, v[78:79], off offset:256
	global_load_dword v92, v[76:77], off offset:512
	global_load_dword v108, v[78:79], off offset:512
	global_load_dword v93, v[76:77], off offset:768
	global_load_dword v109, v[78:79], off offset:768
	global_load_dword v94, v[76:77], off offset:1024
	global_load_dword v111, v[78:79], off offset:1024
	global_load_dword v95, v[76:77], off offset:1280
	global_load_dword v112, v[78:79], off offset:1280
	global_load_dword v96, v[76:77], off offset:1536
	global_load_dword v113, v[78:79], off offset:1536
	global_load_dword v97, v[76:77], off offset:1792
	global_load_dword v114, v[78:79], off offset:1792
	global_load_dword v98, v[76:77], off offset:2048
	global_load_dword v115, v[78:79], off offset:2048
	global_load_dword v99, v[76:77], off offset:2304
	global_load_dword v116, v[78:79], off offset:2304
	global_load_dword v100, v[76:77], off offset:2560
	global_load_dword v117, v[78:79], off offset:2560
	global_load_dword v101, v[76:77], off offset:2816
	global_load_dword v118, v[78:79], off offset:2816
	global_load_dword v102, v[76:77], off offset:3072
	global_load_dword v119, v[78:79], off offset:3072
	global_load_dword v103, v[76:77], off offset:3328
	global_load_dword v120, v[78:79], off offset:3328
	global_load_dword v104, v[76:77], off offset:3584
	global_load_dword v121, v[78:79], off offset:3584
	global_load_dword v105, v[76:77], off offset:3840
	global_load_dword v122, v[78:79], off offset:3840
	v_lshl_add_u64 v[88:89], v[6:7], 0, v[56:57]
	s_waitcnt vmcnt(0)
	v_cvt_f64_f32_e32 v[86:87], v176
	v_cvt_f64_f32_e32 v[80:81], v140
	v_mul_f64 v[82:83], v[74:75], v[80:81]
	v_mul_f64 v[80:81], v[72:73], v[80:81]
	v_fma_f64 v[82:83], v[72:73], v[86:87], -v[82:83]
	v_fmac_f64_e32 v[80:81], v[74:75], v[86:87]
	v_cvt_f32_f64_e32 v176, v[82:83]
	v_cvt_f32_f64_e32 v140, v[80:81]
	v_cvt_f64_f32_e32 v[86:87], v177
	v_cvt_f64_f32_e32 v[80:81], v141
	v_mul_f64 v[82:83], v[74:75], v[80:81]
	v_mul_f64 v[80:81], v[72:73], v[80:81]
	v_fma_f64 v[82:83], v[72:73], v[86:87], -v[82:83]
	v_fmac_f64_e32 v[80:81], v[74:75], v[86:87]
	v_cvt_f32_f64_e32 v177, v[82:83]
	v_cvt_f32_f64_e32 v141, v[80:81]
	v_cvt_f64_f32_e32 v[86:87], v178
	v_cvt_f64_f32_e32 v[80:81], v142
	v_mul_f64 v[82:83], v[74:75], v[80:81]
	v_mul_f64 v[80:81], v[72:73], v[80:81]
	v_fma_f64 v[82:83], v[72:73], v[86:87], -v[82:83]
	v_fmac_f64_e32 v[80:81], v[74:75], v[86:87]
	v_cvt_f32_f64_e32 v178, v[82:83]
	v_cvt_f32_f64_e32 v142, v[80:81]
	v_cvt_f64_f32_e32 v[86:87], v179
	v_cvt_f64_f32_e32 v[80:81], v143
	v_mul_f64 v[82:83], v[74:75], v[80:81]
	v_mul_f64 v[80:81], v[72:73], v[80:81]
	v_fma_f64 v[82:83], v[72:73], v[86:87], -v[82:83]
	v_fmac_f64_e32 v[80:81], v[74:75], v[86:87]
	v_cvt_f32_f64_e32 v179, v[82:83]
	v_cvt_f32_f64_e32 v143, v[80:81]
	v_cvt_f64_f32_e32 v[86:87], v180
	v_cvt_f64_f32_e32 v[80:81], v144
	v_mul_f64 v[82:83], v[74:75], v[80:81]
	v_mul_f64 v[80:81], v[72:73], v[80:81]
	v_fma_f64 v[82:83], v[72:73], v[86:87], -v[82:83]
	v_fmac_f64_e32 v[80:81], v[74:75], v[86:87]
	v_cvt_f32_f64_e32 v180, v[82:83]
	v_cvt_f32_f64_e32 v144, v[80:81]
	v_cvt_f64_f32_e32 v[86:87], v181
	v_cvt_f64_f32_e32 v[80:81], v145
	v_mul_f64 v[82:83], v[74:75], v[80:81]
	v_mul_f64 v[80:81], v[72:73], v[80:81]
	v_fma_f64 v[82:83], v[72:73], v[86:87], -v[82:83]
	v_fmac_f64_e32 v[80:81], v[74:75], v[86:87]
	v_cvt_f32_f64_e32 v181, v[82:83]
	v_cvt_f32_f64_e32 v145, v[80:81]
	v_cvt_f64_f32_e32 v[86:87], v182
	v_cvt_f64_f32_e32 v[80:81], v146
	v_mul_f64 v[82:83], v[74:75], v[80:81]
	v_mul_f64 v[80:81], v[72:73], v[80:81]
	v_fma_f64 v[82:83], v[72:73], v[86:87], -v[82:83]
	v_fmac_f64_e32 v[80:81], v[74:75], v[86:87]
	v_cvt_f32_f64_e32 v182, v[82:83]
	v_cvt_f32_f64_e32 v146, v[80:81]
	v_cvt_f64_f32_e32 v[86:87], v183
	v_cvt_f64_f32_e32 v[80:81], v147
	v_mul_f64 v[82:83], v[74:75], v[80:81]
	v_mul_f64 v[80:81], v[72:73], v[80:81]
	v_fma_f64 v[82:83], v[72:73], v[86:87], -v[82:83]
	v_fmac_f64_e32 v[80:81], v[74:75], v[86:87]
	v_cvt_f32_f64_e32 v183, v[82:83]
	v_cvt_f32_f64_e32 v147, v[80:81]
	v_cvt_f64_f32_e32 v[86:87], v184
	v_cvt_f64_f32_e32 v[80:81], v148
	v_mul_f64 v[82:83], v[74:75], v[80:81]
	v_mul_f64 v[80:81], v[72:73], v[80:81]
	v_fma_f64 v[82:83], v[72:73], v[86:87], -v[82:83]
	v_fmac_f64_e32 v[80:81], v[74:75], v[86:87]
	v_cvt_f32_f64_e32 v184, v[82:83]
	v_cvt_f32_f64_e32 v148, v[80:81]
	v_cvt_f64_f32_e32 v[86:87], v185
	v_cvt_f64_f32_e32 v[80:81], v149
	v_mul_f64 v[82:83], v[74:75], v[80:81]
	v_mul_f64 v[80:81], v[72:73], v[80:81]
	v_fma_f64 v[82:83], v[72:73], v[86:87], -v[82:83]
	v_fmac_f64_e32 v[80:81], v[74:75], v[86:87]
	v_cvt_f32_f64_e32 v185, v[82:83]
	v_cvt_f32_f64_e32 v149, v[80:81]
	v_cvt_f64_f32_e32 v[86:87], v186
	v_cvt_f64_f32_e32 v[80:81], v150
	v_mul_f64 v[82:83], v[74:75], v[80:81]
	v_mul_f64 v[80:81], v[72:73], v[80:81]
	v_fma_f64 v[82:83], v[72:73], v[86:87], -v[82:83]
	v_fmac_f64_e32 v[80:81], v[74:75], v[86:87]
	v_cvt_f32_f64_e32 v186, v[82:83]
	v_cvt_f32_f64_e32 v150, v[80:81]
	v_cvt_f64_f32_e32 v[86:87], v187
	v_cvt_f64_f32_e32 v[80:81], v151
	v_mul_f64 v[82:83], v[74:75], v[80:81]
	v_mul_f64 v[80:81], v[72:73], v[80:81]
	v_fma_f64 v[82:83], v[72:73], v[86:87], -v[82:83]
	v_fmac_f64_e32 v[80:81], v[74:75], v[86:87]
	v_cvt_f32_f64_e32 v187, v[82:83]
	v_cvt_f32_f64_e32 v151, v[80:81]
	v_cvt_f64_f32_e32 v[86:87], v188
	v_cvt_f64_f32_e32 v[80:81], v152
	v_mul_f64 v[82:83], v[74:75], v[80:81]
	v_mul_f64 v[80:81], v[72:73], v[80:81]
	v_fma_f64 v[82:83], v[72:73], v[86:87], -v[82:83]
	v_fmac_f64_e32 v[80:81], v[74:75], v[86:87]
	v_cvt_f32_f64_e32 v188, v[82:83]
	v_cvt_f32_f64_e32 v152, v[80:81]
	v_cvt_f64_f32_e32 v[86:87], v189
	v_cvt_f64_f32_e32 v[80:81], v153
	v_mul_f64 v[82:83], v[74:75], v[80:81]
	v_mul_f64 v[80:81], v[72:73], v[80:81]
	v_fma_f64 v[82:83], v[72:73], v[86:87], -v[82:83]
	v_fmac_f64_e32 v[80:81], v[74:75], v[86:87]
	v_cvt_f32_f64_e32 v189, v[82:83]
	v_cvt_f32_f64_e32 v153, v[80:81]
	v_cvt_f64_f32_e32 v[86:87], v190
	v_cvt_f64_f32_e32 v[80:81], v154
	v_mul_f64 v[82:83], v[74:75], v[80:81]
	v_mul_f64 v[80:81], v[72:73], v[80:81]
	v_fma_f64 v[82:83], v[72:73], v[86:87], -v[82:83]
	v_fmac_f64_e32 v[80:81], v[74:75], v[86:87]
	v_cvt_f32_f64_e32 v190, v[82:83]
	v_cvt_f32_f64_e32 v154, v[80:81]
	v_cvt_f64_f32_e32 v[86:87], v191
	v_cvt_f64_f32_e32 v[80:81], v155
	v_mul_f64 v[82:83], v[74:75], v[80:81]
	v_mul_f64 v[80:81], v[72:73], v[80:81]
	v_fma_f64 v[82:83], v[72:73], v[86:87], -v[82:83]
	v_fmac_f64_e32 v[80:81], v[74:75], v[86:87]
	v_cvt_f32_f64_e32 v191, v[82:83]
	v_cvt_f32_f64_e32 v155, v[80:81]
	global_store_dwordx4 v[62:63], v[176:179], off offset:3072
	global_store_dwordx4 v[64:65], v[140:143], off offset:3072
	global_store_dwordx4 v[62:63], v[180:183], off offset:3088
	global_store_dwordx4 v[64:65], v[144:147], off offset:3088
	global_store_dwordx4 v[62:63], v[184:187], off offset:3104
	global_store_dwordx4 v[64:65], v[148:151], off offset:3104
	global_store_dwordx4 v[62:63], v[188:191], off offset:3120
	global_store_dwordx4 v[64:65], v[152:155], off offset:3120
	v_cvt_pk_bf16_f32 v90, v90, v5
	v_xor_b32_e32 v106, 0x80000000, v106
	v_cvt_pk_bf16_f32 v106, v106, v5
	global_store_short v[88:89], v90, off
	global_store_short v[88:89], v106, off offset:128
	v_cvt_pk_bf16_f32 v91, v91, v5
	v_xor_b32_e32 v107, 0x80000000, v107
	v_cvt_pk_bf16_f32 v107, v107, v5
	global_store_short v[88:89], v91, off offset:256
	global_store_short v[88:89], v107, off offset:384
	v_cvt_pk_bf16_f32 v92, v92, v5
	v_xor_b32_e32 v108, 0x80000000, v108
	v_cvt_pk_bf16_f32 v108, v108, v5
	global_store_short v[88:89], v92, off offset:512
	global_store_short v[88:89], v108, off offset:640
	v_cvt_pk_bf16_f32 v93, v93, v5
	v_xor_b32_e32 v109, 0x80000000, v109
	v_cvt_pk_bf16_f32 v109, v109, v5
	global_store_short v[88:89], v93, off offset:768
	global_store_short v[88:89], v109, off offset:896
	v_cvt_pk_bf16_f32 v94, v94, v5
	v_xor_b32_e32 v111, 0x80000000, v111
	v_cvt_pk_bf16_f32 v111, v111, v5
	global_store_short v[88:89], v94, off offset:1024
	global_store_short v[88:89], v111, off offset:1152
	v_cvt_pk_bf16_f32 v95, v95, v5
	v_xor_b32_e32 v112, 0x80000000, v112
	v_cvt_pk_bf16_f32 v112, v112, v5
	global_store_short v[88:89], v95, off offset:1280
	global_store_short v[88:89], v112, off offset:1408
	v_cvt_pk_bf16_f32 v96, v96, v5
	v_xor_b32_e32 v113, 0x80000000, v113
	v_cvt_pk_bf16_f32 v113, v113, v5
	global_store_short v[88:89], v96, off offset:1536
	global_store_short v[88:89], v113, off offset:1664
	v_cvt_pk_bf16_f32 v97, v97, v5
	v_xor_b32_e32 v114, 0x80000000, v114
	v_cvt_pk_bf16_f32 v114, v114, v5
	global_store_short v[88:89], v97, off offset:1792
	global_store_short v[88:89], v114, off offset:1920
	v_cvt_pk_bf16_f32 v98, v98, v5
	v_xor_b32_e32 v115, 0x80000000, v115
	v_cvt_pk_bf16_f32 v115, v115, v5
	global_store_short v[88:89], v98, off offset:2048
	global_store_short v[88:89], v115, off offset:2176
	v_cvt_pk_bf16_f32 v99, v99, v5
	v_xor_b32_e32 v116, 0x80000000, v116
	v_cvt_pk_bf16_f32 v116, v116, v5
	global_store_short v[88:89], v99, off offset:2304
	global_store_short v[88:89], v116, off offset:2432
	v_cvt_pk_bf16_f32 v100, v100, v5
	v_xor_b32_e32 v117, 0x80000000, v117
	v_cvt_pk_bf16_f32 v117, v117, v5
	global_store_short v[88:89], v100, off offset:2560
	global_store_short v[88:89], v117, off offset:2688
	v_cvt_pk_bf16_f32 v101, v101, v5
	v_xor_b32_e32 v118, 0x80000000, v118
	v_cvt_pk_bf16_f32 v118, v118, v5
	global_store_short v[88:89], v101, off offset:2816
	global_store_short v[88:89], v118, off offset:2944
	v_cvt_pk_bf16_f32 v102, v102, v5
	v_xor_b32_e32 v119, 0x80000000, v119
	v_cvt_pk_bf16_f32 v119, v119, v5
	global_store_short v[88:89], v102, off offset:3072
	global_store_short v[88:89], v119, off offset:3200
	v_cvt_pk_bf16_f32 v103, v103, v5
	v_xor_b32_e32 v120, 0x80000000, v120
	v_cvt_pk_bf16_f32 v120, v120, v5
	global_store_short v[88:89], v103, off offset:3328
	global_store_short v[88:89], v120, off offset:3456
	v_cvt_pk_bf16_f32 v104, v104, v5
	v_xor_b32_e32 v121, 0x80000000, v121
	v_cvt_pk_bf16_f32 v121, v121, v5
	global_store_short v[88:89], v104, off offset:3584
	global_store_short v[88:89], v121, off offset:3712
	v_cvt_pk_bf16_f32 v105, v105, v5
	v_xor_b32_e32 v122, 0x80000000, v122
	v_cvt_pk_bf16_f32 v122, v122, v5
	global_store_short v[88:89], v105, off offset:3840
	global_store_short v[88:89], v122, off offset:3968
	s_andn2_b64 exec, exec, s[22:23]
	s_cbranch_execz .LBB0_135
